# P5b RG-LRU scan: LDS reads batched (2x16 steps in registers) instead of one LDS round trip per step
# speedup vs baseline: 1.0092x; 1.0092x over previous
; #define LAS __attribute__((address_space(3)))
; __global__ void __launch_bounds__(NTHREADS, 2) fwd_kernel(Params P) {
;     ...
;                     LAS float* segA = (LAS float*)(lds + 131072); LAS float* segH = segA + 512;
;                     const int seg = tid >> 7, chn = tid & 127;
;                     float h = 0.f, pa = 1.f;
; #pragma unroll 8
;                     for (int i = 0; i < 32; ++i) { const int o = (32 * seg + i) * 128 + chn; const float a = AARR[o], b = XCF[o]; h = a * h + b; pa *= a; XCF[o] = h; AARR[o] = pa; }
;                     segA[tid] = pa; segH[tid] = h;
;                     __syncthreads();
.LBB0_616:
	v_add_u32_e32 v34, 0x0, v175
	v_add_u32_e32 v35, 0x10000, v34
	ds_read2st64_b32 v[212:213], v34 offset0:0 offset1:2
	ds_read2st64_b32 v[214:215], v34 offset0:4 offset1:6
	ds_read2st64_b32 v[216:217], v34 offset0:8 offset1:10
	ds_read2st64_b32 v[218:219], v34 offset0:12 offset1:14
	ds_read2st64_b32 v[220:221], v34 offset0:16 offset1:18
	ds_read2st64_b32 v[222:223], v34 offset0:20 offset1:22
	ds_read2st64_b32 v[224:225], v34 offset0:24 offset1:26
	ds_read2st64_b32 v[226:227], v34 offset0:28 offset1:30
	ds_read2st64_b32 v[228:229], v35 offset0:0 offset1:2
	ds_read2st64_b32 v[230:231], v35 offset0:4 offset1:6
	ds_read2st64_b32 v[232:233], v35 offset0:8 offset1:10
	ds_read2st64_b32 v[238:239], v35 offset0:12 offset1:14
	ds_read2st64_b32 v[240:241], v35 offset0:16 offset1:18
	ds_read2st64_b32 v[242:243], v35 offset0:20 offset1:22
	ds_read2st64_b32 v[244:245], v35 offset0:24 offset1:26
	ds_read2st64_b32 v[246:247], v35 offset0:28 offset1:30
	s_waitcnt lgkmcnt(0)
	v_fmac_f32_e32 v228, v36, v212
	v_mul_f32_e32 v212, v37, v212
	v_fmac_f32_e32 v229, v228, v213
	v_mul_f32_e32 v213, v212, v213
	v_fmac_f32_e32 v230, v229, v214
	v_mul_f32_e32 v214, v213, v214
	v_fmac_f32_e32 v231, v230, v215
	v_mul_f32_e32 v215, v214, v215
	v_fmac_f32_e32 v232, v231, v216
	v_mul_f32_e32 v216, v215, v216
	v_fmac_f32_e32 v233, v232, v217
	v_mul_f32_e32 v217, v216, v217
	v_fmac_f32_e32 v238, v233, v218
	v_mul_f32_e32 v218, v217, v218
	v_fmac_f32_e32 v239, v238, v219
	v_mul_f32_e32 v219, v218, v219
	v_fmac_f32_e32 v240, v239, v220
	v_mul_f32_e32 v220, v219, v220
	v_fmac_f32_e32 v241, v240, v221
	v_mul_f32_e32 v221, v220, v221
	v_fmac_f32_e32 v242, v241, v222
	v_mul_f32_e32 v222, v221, v222
	v_fmac_f32_e32 v243, v242, v223
	v_mul_f32_e32 v223, v222, v223
	v_fmac_f32_e32 v244, v243, v224
	v_mul_f32_e32 v224, v223, v224
	v_fmac_f32_e32 v245, v244, v225
	v_mul_f32_e32 v225, v224, v225
	v_fmac_f32_e32 v246, v245, v226
	v_mul_f32_e32 v226, v225, v226
	v_fmac_f32_e32 v247, v246, v227
	v_mul_f32_e32 v227, v226, v227
	v_mov_b32_e32 v36, v247
	v_mov_b32_e32 v37, v227
	ds_write2st64_b32 v35, v228, v229 offset0:0 offset1:2
	ds_write2st64_b32 v35, v230, v231 offset0:4 offset1:6
	ds_write2st64_b32 v35, v232, v233 offset0:8 offset1:10
	ds_write2st64_b32 v35, v238, v239 offset0:12 offset1:14
	ds_write2st64_b32 v35, v240, v241 offset0:16 offset1:18
	ds_write2st64_b32 v35, v242, v243 offset0:20 offset1:22
	ds_write2st64_b32 v35, v244, v245 offset0:24 offset1:26
	ds_write2st64_b32 v35, v246, v247 offset0:28 offset1:30
	ds_write2st64_b32 v34, v212, v213 offset0:0 offset1:2
	ds_write2st64_b32 v34, v214, v215 offset0:4 offset1:6
	ds_write2st64_b32 v34, v216, v217 offset0:8 offset1:10
	ds_write2st64_b32 v34, v218, v219 offset0:12 offset1:14
	ds_write2st64_b32 v34, v220, v221 offset0:16 offset1:18
	ds_write2st64_b32 v34, v222, v223 offset0:20 offset1:22
	ds_write2st64_b32 v34, v224, v225 offset0:24 offset1:26
	ds_write2st64_b32 v34, v226, v227 offset0:28 offset1:30
	v_add_u32_e32 v34, 0x2000, v175
	v_add_u32_e32 v35, 0x10000, v34
	ds_read2st64_b32 v[212:213], v34 offset0:0 offset1:2
	ds_read2st64_b32 v[214:215], v34 offset0:4 offset1:6
	ds_read2st64_b32 v[216:217], v34 offset0:8 offset1:10
	ds_read2st64_b32 v[218:219], v34 offset0:12 offset1:14
	ds_read2st64_b32 v[220:221], v34 offset0:16 offset1:18
	ds_read2st64_b32 v[222:223], v34 offset0:20 offset1:22
	ds_read2st64_b32 v[224:225], v34 offset0:24 offset1:26
	ds_read2st64_b32 v[226:227], v34 offset0:28 offset1:30
	ds_read2st64_b32 v[228:229], v35 offset0:0 offset1:2
	ds_read2st64_b32 v[230:231], v35 offset0:4 offset1:6
	ds_read2st64_b32 v[232:233], v35 offset0:8 offset1:10
	ds_read2st64_b32 v[238:239], v35 offset0:12 offset1:14
	ds_read2st64_b32 v[240:241], v35 offset0:16 offset1:18
	ds_read2st64_b32 v[242:243], v35 offset0:20 offset1:22
	ds_read2st64_b32 v[244:245], v35 offset0:24 offset1:26
	ds_read2st64_b32 v[246:247], v35 offset0:28 offset1:30
	s_waitcnt lgkmcnt(0)
	v_fmac_f32_e32 v228, v36, v212
	v_mul_f32_e32 v212, v37, v212
	v_fmac_f32_e32 v229, v228, v213
	v_mul_f32_e32 v213, v212, v213
	v_fmac_f32_e32 v230, v229, v214
	v_mul_f32_e32 v214, v213, v214
	v_fmac_f32_e32 v231, v230, v215
	v_mul_f32_e32 v215, v214, v215
	v_fmac_f32_e32 v232, v231, v216
	v_mul_f32_e32 v216, v215, v216
	v_fmac_f32_e32 v233, v232, v217
	v_mul_f32_e32 v217, v216, v217
	v_fmac_f32_e32 v238, v233, v218
	v_mul_f32_e32 v218, v217, v218
	v_fmac_f32_e32 v239, v238, v219
	v_mul_f32_e32 v219, v218, v219
	v_fmac_f32_e32 v240, v239, v220
	v_mul_f32_e32 v220, v219, v220
	v_fmac_f32_e32 v241, v240, v221
	v_mul_f32_e32 v221, v220, v221
	v_fmac_f32_e32 v242, v241, v222
	v_mul_f32_e32 v222, v221, v222
	v_fmac_f32_e32 v243, v242, v223
	v_mul_f32_e32 v223, v222, v223
	v_fmac_f32_e32 v244, v243, v224
	v_mul_f32_e32 v224, v223, v224
	v_fmac_f32_e32 v245, v244, v225
	v_mul_f32_e32 v225, v224, v225
	v_fmac_f32_e32 v246, v245, v226
	v_mul_f32_e32 v226, v225, v226
	v_fmac_f32_e32 v247, v246, v227
	v_mul_f32_e32 v227, v226, v227
	v_mov_b32_e32 v36, v247
	v_mov_b32_e32 v37, v227
	ds_write2st64_b32 v35, v228, v229 offset0:0 offset1:2
	ds_write2st64_b32 v35, v230, v231 offset0:4 offset1:6
	ds_write2st64_b32 v35, v232, v233 offset0:8 offset1:10
	ds_write2st64_b32 v35, v238, v239 offset0:12 offset1:14
	ds_write2st64_b32 v35, v240, v241 offset0:16 offset1:18
	ds_write2st64_b32 v35, v242, v243 offset0:20 offset1:22
	ds_write2st64_b32 v35, v244, v245 offset0:24 offset1:26
	ds_write2st64_b32 v35, v246, v247 offset0:28 offset1:30
	ds_write2st64_b32 v34, v212, v213 offset0:0 offset1:2
	ds_write2st64_b32 v34, v214, v215 offset0:4 offset1:6
	ds_write2st64_b32 v34, v216, v217 offset0:8 offset1:10
	ds_write2st64_b32 v34, v218, v219 offset0:12 offset1:14
	ds_write2st64_b32 v34, v220, v221 offset0:16 offset1:18
	ds_write2st64_b32 v34, v222, v223 offset0:20 offset1:22
	ds_write2st64_b32 v34, v224, v225 offset0:24 offset1:26
	ds_write2st64_b32 v34, v226, v227 offset0:28 offset1:30
	v_mov_b32_e32 v32, 0
	v_mov_b32_e32 v34, 1.0
	ds_write_b32 v149, v37
	ds_write_b32 v150, v36
	s_waitcnt lgkmcnt(0)
	s_barrier
	s_and_saveexec_b64 s[0:1], s[6:7]
	s_cbranch_execz .LBB0_621
	v_mov_b32_e32 v32, 0
	v_mov_b32_e32 v34, 1.0
	s_mov_b64 s[24:25], 0
	v_mov_b32_e32 v33, v184
	v_mov_b32_e32 v35, v148
